# P0 weight-transpose loops batched (8 rows per round trip); slow-path PV also hand-scheduled
# speedup vs baseline: 1.0236x; 1.0048x over previous
.LBB0_24:
	v_mov_b32_e32 v200, 0x3f24fd5c
	v_mov_b32_e32 v201, 0x3f24fd5c
	v_mov_b32_e32 v202, 0x3f24fd5c
	v_mov_b32_e32 v203, 0x3f24fd5c
	v_mov_b32_e32 v204, 0x3f24fd5c
	v_mov_b32_e32 v205, 0x3f24fd5c
	v_mov_b32_e32 v206, 0x3f24fd5c
	v_mov_b32_e32 v207, 0x3f24fd5c
	s_andn2_b64 vcc, exec, s[4:5]
	s_cbranch_vccnz .Lp0_wo_ng
	v_add_u32_e32 v218, -14, v21
	v_and_b32_e32 v218, 0x7f, v218
	v_lshlrev_b32_e32 v218, 2, v218
	global_load_dword v200, v218, s[26:27]
	v_add_u32_e32 v218, -12, v21
	v_and_b32_e32 v218, 0x7f, v218
	v_lshlrev_b32_e32 v218, 2, v218
	global_load_dword v201, v218, s[26:27]
	v_add_u32_e32 v218, -10, v21
	v_and_b32_e32 v218, 0x7f, v218
	v_lshlrev_b32_e32 v218, 2, v218
	global_load_dword v202, v218, s[26:27]
	v_add_u32_e32 v218, -8, v21
	v_and_b32_e32 v218, 0x7f, v218
	v_lshlrev_b32_e32 v218, 2, v218
	global_load_dword v203, v218, s[26:27]
	v_add_u32_e32 v218, -6, v21
	v_and_b32_e32 v218, 0x7f, v218
	v_lshlrev_b32_e32 v218, 2, v218
	global_load_dword v204, v218, s[26:27]
	v_add_u32_e32 v218, -4, v21
	v_and_b32_e32 v218, 0x7f, v218
	v_lshlrev_b32_e32 v218, 2, v218
	global_load_dword v205, v218, s[26:27]
	v_add_u32_e32 v218, -2, v21
	v_and_b32_e32 v218, 0x7f, v218
	v_lshlrev_b32_e32 v218, 2, v218
	global_load_dword v206, v218, s[26:27]
	v_add_u32_e32 v218, 0, v21
	v_and_b32_e32 v218, 0x7f, v218
	v_lshlrev_b32_e32 v218, 2, v218
	global_load_dword v207, v218, s[26:27]
.Lp0_wo_ng:
	v_lshl_add_u64 v[216:217], v[82:83], 0, s[28:29]
	global_load_dword v208, v[216:217], off
	v_lshl_add_u64 v[216:217], v[80:81], 0, s[28:29]
	global_load_dword v209, v[216:217], off
	v_lshl_add_u64 v[216:217], v[78:79], 0, s[28:29]
	global_load_dword v210, v[216:217], off
	v_lshl_add_u64 v[216:217], v[76:77], 0, s[28:29]
	global_load_dword v211, v[216:217], off
	v_lshl_add_u64 v[216:217], v[74:75], 0, s[28:29]
	global_load_dword v212, v[216:217], off
	v_lshl_add_u64 v[216:217], v[72:73], 0, s[28:29]
	global_load_dword v213, v[216:217], off
	v_lshl_add_u64 v[216:217], v[70:71], 0, s[28:29]
	global_load_dword v214, v[216:217], off
	v_lshl_add_u64 v[216:217], v[68:69], 0, s[28:29]
	global_load_dword v215, v[216:217], off
	s_waitcnt vmcnt(0)
	s_andn2_b64 vcc, exec, s[4:5]
	s_cbranch_vccnz .Lp0_wo_ns
	v_mul_f32_e32 v200, 0x3f24fd5c, v200
	v_mul_f32_e32 v201, 0x3f24fd5c, v201
	v_mul_f32_e32 v202, 0x3f24fd5c, v202
	v_mul_f32_e32 v203, 0x3f24fd5c, v203
	v_mul_f32_e32 v204, 0x3f24fd5c, v204
	v_mul_f32_e32 v205, 0x3f24fd5c, v205
	v_mul_f32_e32 v206, 0x3f24fd5c, v206
	v_mul_f32_e32 v207, 0x3f24fd5c, v207
.Lp0_wo_ns:
	v_mul_f32_e32 v200, v200, v208
	ds_write_b32 v2, v200
	v_mul_f32_e32 v201, v201, v209
	ds_write_b32 v2, v201 offset:264
	v_mul_f32_e32 v202, v202, v210
	ds_write_b32 v2, v202 offset:528
	v_mul_f32_e32 v203, v203, v211
	ds_write_b32 v2, v203 offset:792
	v_mul_f32_e32 v204, v204, v212
	ds_write_b32 v2, v204 offset:1056
	v_mul_f32_e32 v205, v205, v213
	ds_write_b32 v2, v205 offset:1320
	v_mul_f32_e32 v206, v206, v214
	ds_write_b32 v2, v206 offset:1584
	v_mul_f32_e32 v207, v207, v215
	ds_write_b32 v2, v207 offset:1848
	v_add_u32_e32 v2, 0x840, v2
	v_add_u32_e32 v21, 16, v21
	s_add_u32 s28, s28, 0x10000
	s_addc_u32 s29, s29, 0
	s_cmp_lg_u32 s28, 0x40000
	s_cbranch_scc1 .LBB0_24
	s_branch .LBB0_40

.LBB0_50:
	v_mov_b32_e32 v200, 1.0
	v_mov_b32_e32 v201, 1.0
	v_mov_b32_e32 v202, 1.0
	v_mov_b32_e32 v203, 1.0
	v_mov_b32_e32 v204, 1.0
	v_mov_b32_e32 v205, 1.0
	v_mov_b32_e32 v206, 1.0
	v_mov_b32_e32 v207, 1.0
	s_andn2_b64 vcc, exec, s[12:13]
	s_cbranch_vccnz .Lp0_kv_ng
	v_add_u32_e32 v218, -14, v21
	v_and_b32_e32 v218, 0xffff, v218
	v_lshlrev_b32_e32 v218, 2, v218
	global_load_dword v200, v218, s[64:65]
	v_add_u32_e32 v218, -12, v21
	v_and_b32_e32 v218, 0xffff, v218
	v_lshlrev_b32_e32 v218, 2, v218
	global_load_dword v201, v218, s[64:65]
	v_add_u32_e32 v218, -10, v21
	v_and_b32_e32 v218, 0xffff, v218
	v_lshlrev_b32_e32 v218, 2, v218
	global_load_dword v202, v218, s[64:65]
	v_add_u32_e32 v218, -8, v21
	v_and_b32_e32 v218, 0xffff, v218
	v_lshlrev_b32_e32 v218, 2, v218
	global_load_dword v203, v218, s[64:65]
	v_add_u32_e32 v218, -6, v21
	v_and_b32_e32 v218, 0xffff, v218
	v_lshlrev_b32_e32 v218, 2, v218
	global_load_dword v204, v218, s[64:65]
	v_add_u32_e32 v218, -4, v21
	v_and_b32_e32 v218, 0xffff, v218
	v_lshlrev_b32_e32 v218, 2, v218
	global_load_dword v205, v218, s[64:65]
	v_add_u32_e32 v218, -2, v21
	v_and_b32_e32 v218, 0xffff, v218
	v_lshlrev_b32_e32 v218, 2, v218
	global_load_dword v206, v218, s[64:65]
	v_add_u32_e32 v218, 0, v21
	v_and_b32_e32 v218, 0xffff, v218
	v_lshlrev_b32_e32 v218, 2, v218
	global_load_dword v207, v218, s[64:65]
.Lp0_kv_ng:
	v_lshl_add_u64 v[216:217], v[82:83], 0, s[28:29]
	global_load_dword v208, v[216:217], off
	v_lshl_add_u64 v[216:217], v[80:81], 0, s[28:29]
	global_load_dword v209, v[216:217], off
	v_lshl_add_u64 v[216:217], v[78:79], 0, s[28:29]
	global_load_dword v210, v[216:217], off
	v_lshl_add_u64 v[216:217], v[76:77], 0, s[28:29]
	global_load_dword v211, v[216:217], off
	v_lshl_add_u64 v[216:217], v[74:75], 0, s[28:29]
	global_load_dword v212, v[216:217], off
	v_lshl_add_u64 v[216:217], v[72:73], 0, s[28:29]
	global_load_dword v213, v[216:217], off
	v_lshl_add_u64 v[216:217], v[70:71], 0, s[28:29]
	global_load_dword v214, v[216:217], off
	v_lshl_add_u64 v[216:217], v[68:69], 0, s[28:29]
	global_load_dword v215, v[216:217], off
	s_waitcnt vmcnt(0)
	v_mul_f32_e32 v200, v200, v208
	ds_write_b32 v2, v200
	v_mul_f32_e32 v201, v201, v209
	ds_write_b32 v2, v201 offset:264
	v_mul_f32_e32 v202, v202, v210
	ds_write_b32 v2, v202 offset:528
	v_mul_f32_e32 v203, v203, v211
	ds_write_b32 v2, v203 offset:792
	v_mul_f32_e32 v204, v204, v212
	ds_write_b32 v2, v204 offset:1056
	v_mul_f32_e32 v205, v205, v213
	ds_write_b32 v2, v205 offset:1320
	v_mul_f32_e32 v206, v206, v214
	ds_write_b32 v2, v206 offset:1584
	v_mul_f32_e32 v207, v207, v215
	ds_write_b32 v2, v207 offset:1848
	v_add_u32_e32 v2, 0x840, v2
	v_add_u32_e32 v21, 16, v21
	s_add_u32 s28, s28, 0x20000
	s_addc_u32 s29, s29, 0
	s_cmp_lg_u32 s28, 0x80000
	s_cbranch_scc1 .LBB0_50
	s_branch .LBB0_66

.LBB0_86:
	v_mov_b32_e32 v200, 1.0
	v_mov_b32_e32 v201, 1.0
	v_mov_b32_e32 v202, 1.0
	v_mov_b32_e32 v203, 1.0
	v_mov_b32_e32 v204, 1.0
	v_mov_b32_e32 v205, 1.0
	v_mov_b32_e32 v206, 1.0
	v_mov_b32_e32 v207, 1.0
	s_andn2_b64 vcc, exec, s[34:35]
	s_cbranch_vccnz .Lp0_up0_ng
	v_lshl_add_u64 v[216:217], s[42:43], 0, v[96:97]
	global_load_dword v200, v[216:217], off
	v_lshl_add_u64 v[216:217], s[42:43], 0, v[92:93]
	global_load_dword v201, v[216:217], off
	v_lshl_add_u64 v[216:217], s[42:43], 0, v[88:89]
	global_load_dword v202, v[216:217], off
	v_lshl_add_u64 v[216:217], s[42:43], 0, v[84:85]
	global_load_dword v203, v[216:217], off
	v_lshl_add_u64 v[216:217], s[42:43], 0, v[80:81]
	global_load_dword v204, v[216:217], off
	v_lshl_add_u64 v[216:217], s[42:43], 0, v[76:77]
	global_load_dword v205, v[216:217], off
	v_lshl_add_u64 v[216:217], s[42:43], 0, v[72:73]
	global_load_dword v206, v[216:217], off
	v_lshl_add_u64 v[216:217], s[42:43], 0, v[2:3]
	global_load_dword v207, v[216:217], off
.Lp0_up0_ng:
	v_lshl_add_u64 v[216:217], v[94:95], 0, s[28:29]
	global_load_dword v208, v[216:217], off
	v_lshl_add_u64 v[216:217], v[90:91], 0, s[28:29]
	global_load_dword v209, v[216:217], off
	v_lshl_add_u64 v[216:217], v[86:87], 0, s[28:29]
	global_load_dword v210, v[216:217], off
	v_lshl_add_u64 v[216:217], v[82:83], 0, s[28:29]
	global_load_dword v211, v[216:217], off
	v_lshl_add_u64 v[216:217], v[78:79], 0, s[28:29]
	global_load_dword v212, v[216:217], off
	v_lshl_add_u64 v[216:217], v[74:75], 0, s[28:29]
	global_load_dword v213, v[216:217], off
	v_lshl_add_u64 v[216:217], v[70:71], 0, s[28:29]
	global_load_dword v214, v[216:217], off
	v_lshl_add_u64 v[216:217], v[68:69], 0, s[28:29]
	global_load_dword v215, v[216:217], off
	s_waitcnt vmcnt(0)
	v_mul_f32_e32 v200, v200, v208
	ds_write_b32 v21, v200
	v_mul_f32_e32 v201, v201, v209
	ds_write_b32 v21, v201 offset:264
	v_mul_f32_e32 v202, v202, v210
	ds_write_b32 v21, v202 offset:528
	v_mul_f32_e32 v203, v203, v211
	ds_write_b32 v21, v203 offset:792
	v_mul_f32_e32 v204, v204, v212
	ds_write_b32 v21, v204 offset:1056
	v_mul_f32_e32 v205, v205, v213
	ds_write_b32 v21, v205 offset:1320
	v_mul_f32_e32 v206, v206, v214
	ds_write_b32 v21, v206 offset:1584
	v_mul_f32_e32 v207, v207, v215
	ds_write_b32 v21, v207 offset:1848
	v_add_u32_e32 v21, 0x840, v21
	s_add_u32 s28, s28, 0x40000
	s_addc_u32 s29, s29, 0
	s_add_u32 s42, s42, 64
	s_addc_u32 s43, s43, 0
	s_cmp_lg_u32 s28, 0x100000
	s_cbranch_scc1 .LBB0_86
	s_branch .LBB0_102

.LBB0_112:
	v_add_u32_e32 v61, s29, v2
	v_mov_b32_e32 v200, 1.0
	v_mov_b32_e32 v201, 1.0
	v_mov_b32_e32 v202, 1.0
	v_mov_b32_e32 v203, 1.0
	v_mov_b32_e32 v204, 1.0
	v_mov_b32_e32 v205, 1.0
	v_mov_b32_e32 v206, 1.0
	v_mov_b32_e32 v207, 1.0
	s_andn2_b64 vcc, exec, s[68:69]
	s_cbranch_vccnz .Lp0_win_ng
	v_add_u32_e32 v218, 0, v61
	v_and_b32_e32 v218, 0xffff, v218
	v_lshlrev_b32_e32 v218, 2, v218
	global_load_dword v200, v218, s[38:39]
	v_add_u32_e32 v218, 2, v61
	v_and_b32_e32 v218, 0xffff, v218
	v_lshlrev_b32_e32 v218, 2, v218
	global_load_dword v201, v218, s[38:39]
	v_add_u32_e32 v218, 4, v61
	v_and_b32_e32 v218, 0xffff, v218
	v_lshlrev_b32_e32 v218, 2, v218
	global_load_dword v202, v218, s[38:39]
	v_add_u32_e32 v218, 6, v61
	v_and_b32_e32 v218, 0xffff, v218
	v_lshlrev_b32_e32 v218, 2, v218
	global_load_dword v203, v218, s[38:39]
	v_add_u32_e32 v218, 8, v61
	v_and_b32_e32 v218, 0xffff, v218
	v_lshlrev_b32_e32 v218, 2, v218
	global_load_dword v204, v218, s[38:39]
	v_add_u32_e32 v218, 10, v61
	v_and_b32_e32 v218, 0xffff, v218
	v_lshlrev_b32_e32 v218, 2, v218
	global_load_dword v205, v218, s[38:39]
	v_add_u32_e32 v218, 12, v61
	v_and_b32_e32 v218, 0xffff, v218
	v_lshlrev_b32_e32 v218, 2, v218
	global_load_dword v206, v218, s[38:39]
	v_add_u32_e32 v218, 14, v61
	v_and_b32_e32 v218, 0xffff, v218
	v_lshlrev_b32_e32 v218, 2, v218
	global_load_dword v207, v218, s[38:39]
.Lp0_win_ng:
	v_add_u32_e32 v218, 0, v61
	v_mad_i64_i32 v[216:217], vcc, v218, s66, v[68:69]
	global_load_dword v208, v[216:217], off
	v_add_u32_e32 v218, 2, v61
	v_mad_i64_i32 v[216:217], vcc, v218, s66, v[68:69]
	global_load_dword v209, v[216:217], off
	v_add_u32_e32 v218, 4, v61
	v_mad_i64_i32 v[216:217], vcc, v218, s66, v[68:69]
	global_load_dword v210, v[216:217], off
	v_add_u32_e32 v218, 6, v61
	v_mad_i64_i32 v[216:217], vcc, v218, s66, v[68:69]
	global_load_dword v211, v[216:217], off
	v_add_u32_e32 v218, 8, v61
	v_mad_i64_i32 v[216:217], vcc, v218, s66, v[68:69]
	global_load_dword v212, v[216:217], off
	v_add_u32_e32 v218, 10, v61
	v_mad_i64_i32 v[216:217], vcc, v218, s66, v[68:69]
	global_load_dword v213, v[216:217], off
	v_add_u32_e32 v218, 12, v61
	v_mad_i64_i32 v[216:217], vcc, v218, s66, v[68:69]
	global_load_dword v214, v[216:217], off
	v_add_u32_e32 v218, 14, v61
	v_mad_i64_i32 v[216:217], vcc, v218, s66, v[68:69]
	global_load_dword v215, v[216:217], off
	s_waitcnt vmcnt(0)
	v_mul_f32_e32 v200, v200, v208
	ds_write_b32 v21, v200
	v_mul_f32_e32 v201, v201, v209
	ds_write_b32 v21, v201 offset:264
	v_mul_f32_e32 v202, v202, v210
	ds_write_b32 v21, v202 offset:528
	v_mul_f32_e32 v203, v203, v211
	ds_write_b32 v21, v203 offset:792
	v_mul_f32_e32 v204, v204, v212
	ds_write_b32 v21, v204 offset:1056
	v_mul_f32_e32 v205, v205, v213
	ds_write_b32 v21, v205 offset:1320
	v_mul_f32_e32 v206, v206, v214
	ds_write_b32 v21, v206 offset:1584
	v_mul_f32_e32 v207, v207, v215
	ds_write_b32 v21, v207 offset:1848
	v_add_u32_e32 v21, 0x840, v21
	s_add_i32 s29, s29, 16
	s_cmp_lg_u32 s29, 64
	s_cbranch_scc1 .LBB0_112
	s_branch .LBB0_5

.LBB0_1315:
	s_and_b32 s4, s95, 3
	s_lshl_b32 s4, s4, 14
	v_add_u32_e32 v243, s4, v7
	v_add_u32_e32 v244, s4, v9
	v_add_u32_e32 v245, s4, v10
	v_add_u32_e32 v246, s4, v11
	ds_read_b64_tr_b16 v[188:189], v243 offset:49152
	ds_read_b64_tr_b16 v[190:191], v243 offset:51200
	ds_read_b64_tr_b16 v[192:193], v244
	ds_read_b64_tr_b16 v[194:195], v244 offset:2048
	ds_read_b64_tr_b16 v[196:197], v245
	ds_read_b64_tr_b16 v[198:199], v245 offset:2048
	ds_read_b64_tr_b16 v[200:201], v246
	ds_read_b64_tr_b16 v[202:203], v246 offset:2048
	v_exp_f32_e32 v228, v96
	v_exp_f32_e32 v229, v97
	v_exp_f32_e32 v230, v98
	v_exp_f32_e32 v231, v99
	v_exp_f32_e32 v232, v100
	v_exp_f32_e32 v233, v101
	v_exp_f32_e32 v234, v102
	v_exp_f32_e32 v187, v103
	v_cvt_pk_bf16_f32 v220, v228, v229
	v_cvt_pk_bf16_f32 v221, v230, v231
	v_cvt_pk_bf16_f32 v222, v232, v233
	v_cvt_pk_bf16_f32 v223, v234, v187
	ds_read_b64_tr_b16 v[204:205], v243 offset:53248
	ds_read_b64_tr_b16 v[206:207], v243 offset:55296
	ds_read_b64_tr_b16 v[208:209], v244 offset:4096
	ds_read_b64_tr_b16 v[210:211], v244 offset:6144
	ds_read_b64_tr_b16 v[212:213], v245 offset:4096
	ds_read_b64_tr_b16 v[214:215], v245 offset:6144
	ds_read_b64_tr_b16 v[216:217], v246 offset:4096
	ds_read_b64_tr_b16 v[218:219], v246 offset:6144
	s_waitcnt lgkmcnt(8)
	v_mfma_f32_32x32x16_bf16 v[80:95], v[188:191], v[220:223], v[80:95]
	ds_read_b64_tr_b16 v[188:189], v243 offset:57344
	ds_read_b64_tr_b16 v[190:191], v243 offset:59392
	v_exp_f32_e32 v247, v104
	v_exp_f32_e32 v248, v105
	v_add_f32_e32 v153, 0, v228
	v_add_f32_e32 v153, v229, v153
	v_mfma_f32_32x32x16_bf16 v[64:79], v[192:195], v[220:223], v[64:79]
	ds_read_b64_tr_b16 v[192:193], v244 offset:8192
	ds_read_b64_tr_b16 v[194:195], v244 offset:10240
	v_exp_f32_e32 v249, v106
	v_exp_f32_e32 v250, v107
	v_add_f32_e32 v153, v230, v153
	v_add_f32_e32 v153, v231, v153
	v_mfma_f32_32x32x16_bf16 v[48:63], v[196:199], v[220:223], v[48:63]
	ds_read_b64_tr_b16 v[196:197], v245 offset:8192
	ds_read_b64_tr_b16 v[198:199], v245 offset:10240
	v_exp_f32_e32 v251, v108
	v_exp_f32_e32 v252, v109
	v_add_f32_e32 v153, v232, v153
	v_add_f32_e32 v153, v233, v153
	v_mfma_f32_32x32x16_bf16 v[32:47], v[200:203], v[220:223], v[32:47]
	ds_read_b64_tr_b16 v[200:201], v246 offset:8192
	ds_read_b64_tr_b16 v[202:203], v246 offset:10240
	v_exp_f32_e32 v253, v110
	v_exp_f32_e32 v254, v111
	v_cvt_pk_bf16_f32 v224, v247, v248
	v_cvt_pk_bf16_f32 v225, v249, v250
	v_cvt_pk_bf16_f32 v226, v251, v252
	v_cvt_pk_bf16_f32 v227, v253, v254
	v_add_f32_e32 v153, v234, v153
	v_add_f32_e32 v153, v187, v153
	s_waitcnt lgkmcnt(8)
	v_mfma_f32_32x32x16_bf16 v[80:95], v[204:207], v[224:227], v[80:95]
	ds_read_b64_tr_b16 v[204:205], v243 offset:61440
	ds_read_b64_tr_b16 v[206:207], v243 offset:63488
	v_exp_f32_e32 v228, v112
	v_exp_f32_e32 v229, v113
	v_add_f32_e32 v153, v247, v153
	v_add_f32_e32 v153, v248, v153
	v_mfma_f32_32x32x16_bf16 v[64:79], v[208:211], v[224:227], v[64:79]
	ds_read_b64_tr_b16 v[208:209], v244 offset:12288
	ds_read_b64_tr_b16 v[210:211], v244 offset:14336
	v_exp_f32_e32 v230, v114
	v_exp_f32_e32 v231, v115
	v_add_f32_e32 v153, v249, v153
	v_add_f32_e32 v153, v250, v153
	v_mfma_f32_32x32x16_bf16 v[48:63], v[212:215], v[224:227], v[48:63]
	ds_read_b64_tr_b16 v[212:213], v245 offset:12288
	ds_read_b64_tr_b16 v[214:215], v245 offset:14336
	v_exp_f32_e32 v232, v116
	v_exp_f32_e32 v233, v117
	v_add_f32_e32 v153, v251, v153
	v_add_f32_e32 v153, v252, v153
	v_mfma_f32_32x32x16_bf16 v[32:47], v[216:219], v[224:227], v[32:47]
	ds_read_b64_tr_b16 v[216:217], v246 offset:12288
	ds_read_b64_tr_b16 v[218:219], v246 offset:14336
	v_exp_f32_e32 v234, v118
	v_exp_f32_e32 v187, v119
	v_cvt_pk_bf16_f32 v220, v228, v229
	v_cvt_pk_bf16_f32 v221, v230, v231
	v_cvt_pk_bf16_f32 v222, v232, v233
	v_cvt_pk_bf16_f32 v223, v234, v187
	v_add_f32_e32 v153, v253, v153
	v_add_f32_e32 v153, v254, v153
	s_waitcnt lgkmcnt(8)
	v_mfma_f32_32x32x16_bf16 v[80:95], v[188:191], v[220:223], v[80:95]
	v_exp_f32_e32 v247, v120
	v_exp_f32_e32 v248, v121
	v_add_f32_e32 v153, v228, v153
	v_add_f32_e32 v153, v229, v153
	v_mfma_f32_32x32x16_bf16 v[64:79], v[192:195], v[220:223], v[64:79]
	v_exp_f32_e32 v249, v122
	v_exp_f32_e32 v250, v123
	v_add_f32_e32 v153, v230, v153
	v_add_f32_e32 v153, v231, v153
	v_mfma_f32_32x32x16_bf16 v[48:63], v[196:199], v[220:223], v[48:63]
	v_exp_f32_e32 v251, v124
	v_exp_f32_e32 v252, v125
	v_add_f32_e32 v153, v232, v153
	v_add_f32_e32 v153, v233, v153
	v_mfma_f32_32x32x16_bf16 v[32:47], v[200:203], v[220:223], v[32:47]
	v_exp_f32_e32 v253, v126
	v_exp_f32_e32 v254, v127
	v_cvt_pk_bf16_f32 v224, v247, v248
	v_cvt_pk_bf16_f32 v225, v249, v250
	v_cvt_pk_bf16_f32 v226, v251, v252
	v_cvt_pk_bf16_f32 v227, v253, v254
	v_add_f32_e32 v153, v234, v153
	v_add_f32_e32 v153, v187, v153
	s_waitcnt lgkmcnt(0)
	v_mfma_f32_32x32x16_bf16 v[80:95], v[204:207], v[224:227], v[80:95]
	v_add_f32_e32 v153, v247, v153
	v_add_f32_e32 v153, v248, v153
	v_mfma_f32_32x32x16_bf16 v[64:79], v[208:211], v[224:227], v[64:79]
	v_add_f32_e32 v153, v249, v153
	v_add_f32_e32 v153, v250, v153
	v_mfma_f32_32x32x16_bf16 v[48:63], v[212:215], v[224:227], v[48:63]
	v_add_f32_e32 v153, v251, v153
	v_add_f32_e32 v153, v252, v153
	v_mfma_f32_32x32x16_bf16 v[32:47], v[216:219], v[224:227], v[32:47]
	v_add_f32_e32 v153, v253, v153
	v_add_f32_e32 v153, v254, v153
	v_add_f32_e32 v6, v6, v153
	s_andn2_b64 vcc, exec, s[74:75]
	s_mov_b64 s[4:5], -1
	s_cbranch_vccz .LBB0_1309

.Latt_flA_top:
	s_lshl_b32 s6, s8, 14
	v_add_u32_e32 v228, s6, v163
	v_add_u32_e32 v229, s6, v164
	v_add_u32_e32 v230, s6, v165
	v_add_u32_e32 v231, s6, v166
	ds_read_b128 v[96:99], v228
	ds_read_b128 v[200:203], v229
	ds_read_b128 v[204:207], v230
	ds_read_b128 v[208:211], v231
	ds_read_b128 v[112:115], v228 offset:8192
	ds_read_b128 v[216:219], v229 offset:8192
	ds_read_b128 v[220:223], v230 offset:8192
	ds_read_b128 v[224:227], v231 offset:8192
	s_add_u32 s98, s0, s72
	s_addc_u32 s99, s1, s73
	s_lshl_b32 s4, s88, 14
	s_add_i32 s5, s87, s4
	s_mov_b32 m0, s5
	s_add_i32 s4, s95, 2
	s_and_b32 s4, s4, 3
	s_lshl_b32 s4, s4, 14
	s_add_i32 s4, s85, s4
	s_waitcnt lgkmcnt(7)
	v_mfma_f32_32x32x16_bf16 v[96:111], v[96:99], v[132:135], 0
	s_waitcnt lgkmcnt(6)
	v_mfma_f32_32x32x16_bf16 v[96:111], v[200:203], v[136:139], v[96:111]
	s_waitcnt lgkmcnt(5)
	v_mfma_f32_32x32x16_bf16 v[96:111], v[204:207], v[140:143], v[96:111]
	s_waitcnt lgkmcnt(4)
	v_mfma_f32_32x32x16_bf16 v[96:111], v[208:211], v[144:147], v[96:111]
	s_waitcnt lgkmcnt(3)
	v_mfma_f32_32x32x16_bf16 v[112:127], v[112:115], v[132:135], 0
	global_load_lds_dwordx4 v239, s[98:99]
	s_addk_i32 s5, 0x400
	s_mov_b32 m0, s5
	s_waitcnt lgkmcnt(2)
	v_mfma_f32_32x32x16_bf16 v[112:127], v[216:219], v[136:139], v[112:127]
	global_load_lds_dwordx4 v240, s[98:99]
	s_add_u32 s98, s66, s72
	s_addc_u32 s99, s67, s73
	s_mov_b32 m0, s4
	s_addk_i32 s4, 0x400
	s_waitcnt lgkmcnt(1)
	v_mfma_f32_32x32x16_bf16 v[112:127], v[220:223], v[140:143], v[112:127]
	global_load_lds_dwordx4 v241, s[98:99]
	s_mov_b32 m0, s4
	s_waitcnt lgkmcnt(0)
	v_mfma_f32_32x32x16_bf16 v[112:127], v[224:227], v[144:147], v[112:127]
	global_load_lds_dwordx4 v242, s[98:99]
	s_and_b32 s7, s95, 3
	s_lshl_b32 s7, s7, 14
	v_add_u32_e32 v243, s7, v7
	v_add_u32_e32 v244, s7, v9
	v_add_u32_e32 v245, s7, v10
	v_add_u32_e32 v246, s7, v11
	ds_read_b64_tr_b16 v[188:189], v243 offset:49152
	ds_read_b64_tr_b16 v[190:191], v243 offset:51200
	ds_read_b64_tr_b16 v[192:193], v244
	ds_read_b64_tr_b16 v[194:195], v244 offset:2048
	ds_read_b64_tr_b16 v[196:197], v245
	ds_read_b64_tr_b16 v[198:199], v245 offset:2048
	ds_read_b64_tr_b16 v[200:201], v246
	ds_read_b64_tr_b16 v[202:203], v246 offset:2048
	v_exp_f32_e32 v228, v96
	v_exp_f32_e32 v229, v97
	v_exp_f32_e32 v230, v98
	v_exp_f32_e32 v231, v99
	v_exp_f32_e32 v232, v100
	v_exp_f32_e32 v233, v101
	v_exp_f32_e32 v234, v102
	v_exp_f32_e32 v187, v103
	v_cvt_pk_bf16_f32 v220, v228, v229
	v_cvt_pk_bf16_f32 v221, v230, v231
	v_cvt_pk_bf16_f32 v222, v232, v233
	v_cvt_pk_bf16_f32 v223, v234, v187
	ds_read_b64_tr_b16 v[204:205], v243 offset:53248
	ds_read_b64_tr_b16 v[206:207], v243 offset:55296
	ds_read_b64_tr_b16 v[208:209], v244 offset:4096
	ds_read_b64_tr_b16 v[210:211], v244 offset:6144
	ds_read_b64_tr_b16 v[212:213], v245 offset:4096
	ds_read_b64_tr_b16 v[214:215], v245 offset:6144
	ds_read_b64_tr_b16 v[216:217], v246 offset:4096
	ds_read_b64_tr_b16 v[218:219], v246 offset:6144
	s_waitcnt lgkmcnt(8)
	v_mfma_f32_32x32x16_bf16 v[80:95], v[188:191], v[220:223], v[80:95]
	ds_read_b64_tr_b16 v[188:189], v243 offset:57344
	ds_read_b64_tr_b16 v[190:191], v243 offset:59392
	v_exp_f32_e32 v247, v104
	v_exp_f32_e32 v248, v105
	v_add_f32_e32 v153, 0, v228
	v_add_f32_e32 v153, v229, v153
	v_mfma_f32_32x32x16_bf16 v[64:79], v[192:195], v[220:223], v[64:79]
	ds_read_b64_tr_b16 v[192:193], v244 offset:8192
	ds_read_b64_tr_b16 v[194:195], v244 offset:10240
	v_exp_f32_e32 v249, v106
	v_exp_f32_e32 v250, v107
	v_add_f32_e32 v153, v230, v153
	v_add_f32_e32 v153, v231, v153
	v_mfma_f32_32x32x16_bf16 v[48:63], v[196:199], v[220:223], v[48:63]
	ds_read_b64_tr_b16 v[196:197], v245 offset:8192
	ds_read_b64_tr_b16 v[198:199], v245 offset:10240
	v_exp_f32_e32 v251, v108
	v_exp_f32_e32 v252, v109
	v_add_f32_e32 v153, v232, v153
	v_add_f32_e32 v153, v233, v153
	v_mfma_f32_32x32x16_bf16 v[32:47], v[200:203], v[220:223], v[32:47]
	ds_read_b64_tr_b16 v[200:201], v246 offset:8192
	ds_read_b64_tr_b16 v[202:203], v246 offset:10240
	v_exp_f32_e32 v253, v110
	v_exp_f32_e32 v254, v111
	v_cvt_pk_bf16_f32 v224, v247, v248
	v_cvt_pk_bf16_f32 v225, v249, v250
	v_cvt_pk_bf16_f32 v226, v251, v252
	v_cvt_pk_bf16_f32 v227, v253, v254
	v_add_f32_e32 v153, v234, v153
	v_add_f32_e32 v153, v187, v153
	s_waitcnt lgkmcnt(8)
	v_mfma_f32_32x32x16_bf16 v[80:95], v[204:207], v[224:227], v[80:95]
	ds_read_b64_tr_b16 v[204:205], v243 offset:61440
	ds_read_b64_tr_b16 v[206:207], v243 offset:63488
	v_exp_f32_e32 v228, v112
	v_exp_f32_e32 v229, v113
	v_add_f32_e32 v153, v247, v153
	v_add_f32_e32 v153, v248, v153
	v_mfma_f32_32x32x16_bf16 v[64:79], v[208:211], v[224:227], v[64:79]
	ds_read_b64_tr_b16 v[208:209], v244 offset:12288
	ds_read_b64_tr_b16 v[210:211], v244 offset:14336
	v_exp_f32_e32 v230, v114
	v_exp_f32_e32 v231, v115
	v_add_f32_e32 v153, v249, v153
	v_add_f32_e32 v153, v250, v153
	v_mfma_f32_32x32x16_bf16 v[48:63], v[212:215], v[224:227], v[48:63]
	ds_read_b64_tr_b16 v[212:213], v245 offset:12288
	ds_read_b64_tr_b16 v[214:215], v245 offset:14336
	v_exp_f32_e32 v232, v116
	v_exp_f32_e32 v233, v117
	v_add_f32_e32 v153, v251, v153
	v_add_f32_e32 v153, v252, v153
	v_mfma_f32_32x32x16_bf16 v[32:47], v[216:219], v[224:227], v[32:47]
	ds_read_b64_tr_b16 v[216:217], v246 offset:12288
	ds_read_b64_tr_b16 v[218:219], v246 offset:14336
	v_exp_f32_e32 v234, v118
	v_exp_f32_e32 v187, v119
	v_cvt_pk_bf16_f32 v220, v228, v229
	v_cvt_pk_bf16_f32 v221, v230, v231
	v_cvt_pk_bf16_f32 v222, v232, v233
	v_cvt_pk_bf16_f32 v223, v234, v187
	v_add_f32_e32 v153, v253, v153
	v_add_f32_e32 v153, v254, v153
	s_waitcnt lgkmcnt(8)
	v_mfma_f32_32x32x16_bf16 v[80:95], v[188:191], v[220:223], v[80:95]
	v_exp_f32_e32 v247, v120
	v_exp_f32_e32 v248, v121
	v_add_f32_e32 v153, v228, v153
	v_add_f32_e32 v153, v229, v153
	v_mfma_f32_32x32x16_bf16 v[64:79], v[192:195], v[220:223], v[64:79]
	v_exp_f32_e32 v249, v122
	v_exp_f32_e32 v250, v123
	v_add_f32_e32 v153, v230, v153
	v_add_f32_e32 v153, v231, v153
	v_mfma_f32_32x32x16_bf16 v[48:63], v[196:199], v[220:223], v[48:63]
	v_exp_f32_e32 v251, v124
	v_exp_f32_e32 v252, v125
	v_add_f32_e32 v153, v232, v153
	v_add_f32_e32 v153, v233, v153
	v_mfma_f32_32x32x16_bf16 v[32:47], v[200:203], v[220:223], v[32:47]
	v_exp_f32_e32 v253, v126
	v_exp_f32_e32 v254, v127
	v_cvt_pk_bf16_f32 v224, v247, v248
	v_cvt_pk_bf16_f32 v225, v249, v250
	v_cvt_pk_bf16_f32 v226, v251, v252
	v_cvt_pk_bf16_f32 v227, v253, v254
	v_add_f32_e32 v153, v234, v153
	v_add_f32_e32 v153, v187, v153
	s_waitcnt lgkmcnt(0)
	v_mfma_f32_32x32x16_bf16 v[80:95], v[204:207], v[224:227], v[80:95]
	v_add_f32_e32 v153, v247, v153
	v_add_f32_e32 v153, v248, v153
	v_mfma_f32_32x32x16_bf16 v[64:79], v[208:211], v[224:227], v[64:79]
	v_add_f32_e32 v153, v249, v153
	v_add_f32_e32 v153, v250, v153
	v_mfma_f32_32x32x16_bf16 v[48:63], v[212:215], v[224:227], v[48:63]
	v_add_f32_e32 v153, v251, v153
	v_add_f32_e32 v153, v252, v153
	v_mfma_f32_32x32x16_bf16 v[32:47], v[216:219], v[224:227], v[32:47]
	v_add_f32_e32 v153, v253, v153
	v_add_f32_e32 v153, v254, v153
	v_add_f32_e32 v6, v6, v153
	s_add_u32 s72, s72, 0x20000
	s_addc_u32 s73, s73, 0
	s_add_i32 s95, s95, 1
	s_mov_b32 s71, s8
	s_mov_b32 s8, s78
	s_mov_b32 s78, s88
	s_mov_b32 s88, s71
	s_sub_i32 s101, s101, 1
	s_cmp_lg_u32 s101, 0
	s_waitcnt vmcnt(4) lgkmcnt(0)
	s_barrier
	s_cbranch_scc1 .Latt_flA_top
	s_lshl_b32 s4, s100, 6
	s_sub_i32 s33, s33, s4
	s_sub_i32 s93, s93, s4
	s_sub_u32 s90, s90, s4
	s_subb_u32 s91, s91, 0
	v_add_u32_e32 v179, s4, v179
	s_branch .Latt_slow
